# WC1: layer-0 W_in conversion tiles issue their four 16-byte loads together (one wait) before the LDS scatter instead of load-wait-scatter four times
# speedup vs baseline: 1.0006x; 1.0006x over previous
.LBB0_414:
	s_lshl_b32 s1, s0, 2
	s_lshl_b32 s2, s0, 7
	s_andn2_b32 s1, s1, 63
	s_and_b32 s8, s2, 0x780
	s_and_saveexec_b64 s[2:3], vcc
	s_cbranch_execz .LBB0_419
	v_and_b32_e32 v12, 60, v7
	v_or_b32_e32 v4, s1, v12
	v_ashrrev_i32_e32 v11, 4, v6
	v_cmp_gt_i32_e64 s[40:41], s84, v4
	v_mov_b32_e32 v14, 0
	v_mov_b32_e32 v15, 0
	v_mov_b32_e32 v16, 0
	v_mov_b32_e32 v17, 0
	v_mov_b32_e32 v18, 0
	v_mov_b32_e32 v19, 0
	v_mov_b32_e32 v20, 0
	v_mov_b32_e32 v21, 0
	v_mov_b32_e32 v22, 0
	v_mov_b32_e32 v23, 0
	v_mov_b32_e32 v24, 0
	v_mov_b32_e32 v25, 0
	v_mov_b32_e32 v26, 0
	v_mov_b32_e32 v27, 0
	v_mov_b32_e32 v28, 0
	v_mov_b32_e32 v29, 0
	s_and_saveexec_b64 s[6:7], s[40:41]
	s_cbranch_execz .Lwc1_ld
	v_add_u32_e32 v2, s8, v11
	v_mov_b64_e32 v[0:1], s[64:65]
	s_movk_i32 s9, 0x70c0
	v_mad_i64_i32 v[0:1], s[10:11], v2, s9, v[0:1]
	v_ashrrev_i32_e32 v5, 31, v4
	v_lshl_add_u64 v[0:1], v[4:5], 2, v[0:1]
	s_mov_b64 s[4:5], 0xe1800
	global_load_dwordx4 v[14:17], v[0:1], off
	v_lshl_add_u64 v[0:1], v[0:1], 0, s[4:5]
	global_load_dwordx4 v[18:21], v[0:1], off
	v_lshl_add_u64 v[0:1], v[0:1], 0, s[4:5]
	global_load_dwordx4 v[22:25], v[0:1], off
	v_lshl_add_u64 v[0:1], v[0:1], 0, s[4:5]
	global_load_dwordx4 v[26:29], v[0:1], off
.Lwc1_ld:
	s_or_b64 exec, exec, s[6:7]
	v_mul_lo_u32 v4, v11, s22
	v_lshlrev_b32_e32 v5, 2, v12
	v_add3_u32 v4, 0, v4, v5
	s_waitcnt vmcnt(3)
	ds_write2_b32 v4, v14, v15 offset1:1
	ds_write2_b32 v4, v16, v17 offset0:2 offset1:3
	v_add_u32_e32 v4, 0x2080, v4
	s_waitcnt vmcnt(2)
	ds_write2_b32 v4, v18, v19 offset1:1
	ds_write2_b32 v4, v20, v21 offset0:2 offset1:3
	v_add_u32_e32 v4, 0x2080, v4
	s_waitcnt vmcnt(1)
	ds_write2_b32 v4, v22, v23 offset1:1
	ds_write2_b32 v4, v24, v25 offset0:2 offset1:3
	v_add_u32_e32 v4, 0x2080, v4
	s_waitcnt vmcnt(0)
	ds_write2_b32 v4, v26, v27 offset1:1
	ds_write2_b32 v4, v28, v29 offset0:2 offset1:3
